# attention: second half of each XCD's workgroups walk the queues in order 1,0,2 so that CU partners start on different unit kinds
# baseline (speedup 1.0000x reference)
; #define LAS __attribute__((address_space(3)))
; __global__ void __launch_bounds__(NTHREADS, 2) mega(Params p_, int ph_lo, int ph_hi) {
;     const Params& p = *(const Params*)__builtin_amdgcn_kernarg_segment_ptr();
;     extern __shared__ __attribute__((aligned(16))) char smem[];
;     cg::grid_group grid = cg::this_grid();
;     __shared__ uint4 xb_words;
;     if (threadIdx.x == 0) xb_words = make_uint4(0u, 0u, 0u, 0u);
;     __syncthreads();
;     XcdBarrier xb = xcd_barrier_post(p.bar, (volatile LAS unsigned*)&xb_words);
;     for (int ph = ph_lo; ph < ph_hi; ++ph) {
.LBB0_5:
	s_or_b64 exec, exec, s[4:5]
	s_load_dwordx2 s[52:53], s[0:1], 0x110
	s_waitcnt lgkmcnt(0)
	s_cmp_ge_i32 s52, s53
	s_cbranch_scc1 .LBB0_416
	v_writelane_b32 v255, 0, 44
	s_cmpk_lg_i32 s66, 0x200
	s_cselect_b64 s[4:5], -1, 0
	v_writelane_b32 v254, s4, 3
	s_mul_i32 s7, s67, s66
	s_mov_b32 s75, 0
	v_writelane_b32 v254, s5, 4
	s_mov_b32 s15, s75
	v_readlane_b32 s13, v254, 0
	s_and_b32 s14, s13, 7
	s_lshr_b32 s8, s13, 3
	s_cmpk_lt_i32 s13, 0x480
	s_cselect_b64 s[4:5], -1, 0
	v_writelane_b32 v254, s4, 5
	s_mul_i32 s16, s14, 0x900
	s_mul_hi_u32 s12, s8, 0x1c71c71d
	v_writelane_b32 v254, s5, 6
	s_add_u32 s4, s0, 0xb0
	s_addc_u32 s5, s1, 0
	v_writelane_b32 v254, s4, 7
	s_mul_i32 s12, s12, 9
	s_mul_i32 s11, s14, 9
	v_writelane_b32 v254, s5, 8
	s_add_u32 s4, s0, 0xa8
	s_addc_u32 s5, s1, 0
	v_writelane_b32 v254, s4, 9
	s_mov_b32 s19, s75
	v_lshrrev_b32_e32 v1, 20, v0
	v_writelane_b32 v254, s5, 10
	s_add_u32 s4, s0, 16
	s_addc_u32 s5, s1, 0
	v_writelane_b32 v254, s4, 11
	s_lshl_b32 s2, s8, 4
	v_lshrrev_b32_e32 v0, 10, v0
	v_writelane_b32 v254, s5, 12
	v_writelane_b32 v254, s2, 13
	s_lshl_b32 s2, s13, 4
	s_and_b32 s6, s2, 0x380
	s_lshl_b32 s2, s6, 6
	s_cmpk_lt_u32 s13, 0x100
	v_writelane_b32 v254, s2, 14
	s_cselect_b64 s[4:5], -1, 0
	v_writelane_b32 v254, s4, 15
	s_and_b32 s2, s13, 0x80
	s_lshl_b32 s18, s14, 20
	v_writelane_b32 v254, s5, 16
	s_lshl_b32 s4, s13, 3
	s_and_b32 s5, s4, 64
	s_or_b32 s9, s2, s5
	s_and_b32 s2, s4, 0x380
	s_or_b32 s5, s9, 0x800
	s_lshl_b32 s4, s2, 6
	v_writelane_b32 v254, s4, 17
	s_add_i32 s4, s5, s16
	s_lshl_b32 s10, s4, 5
	s_lshl_b32 s20, s14, 23
	s_cmpk_gt_u32 s13, 0x1f7
	v_writelane_b32 v254, s5, 18
	s_cselect_b64 s[4:5], -1, 0
	s_sub_i32 s8, s8, s12
	s_add_i32 s8, s11, s8
	v_writelane_b32 v254, s8, 19
	s_mul_i32 s8, s13, 0xe38f
	s_lshr_b32 s8, s8, 22
	v_writelane_b32 v254, s8, 20
	s_lshl_b32 s8, s13, 2
	v_writelane_b32 v254, s8, 21
	s_lshl_b32 s8, s66, 2
	s_cmpk_lt_i32 s13, 0x1380
	v_writelane_b32 v254, s8, 22
	s_cselect_b64 s[22:23], -1, 0
	v_writelane_b32 v254, s22, 23
	s_lshl_b32 s8, s13, 8
	s_lshl_b32 s79, s66, 8
	v_writelane_b32 v254, s23, 24
	v_writelane_b32 v254, s8, 25
	s_cmp_eq_u32 s13, 0
	s_load_dword s8, s[0:1], 0x120
	s_cselect_b64 s[12:13], -1, 0
	v_writelane_b32 v254, s12, 26
	s_cmp_lt_i32 s53, 18
	v_or_b32_e32 v0, v0, v1
	v_writelane_b32 v254, s13, 27
	s_cselect_b64 s[12:13], -1, 0
	v_writelane_b32 v254, s12, 28
	s_waitcnt lgkmcnt(0)
; #define LAS __attribute__((address_space(3)))
; DI unsigned xb_ld(unsigned* p)              { return __hip_atomic_load(p, __ATOMIC_RELAXED, __HIP_MEMORY_SCOPE_AGENT); }
; DI unsigned xb_add(unsigned* p, unsigned v) { return __hip_atomic_fetch_add(p, v, __ATOMIC_RELAXED, __HIP_MEMORY_SCOPE_AGENT); }
; DI unsigned xb_xcc_id() { return (unsigned)__builtin_amdgcn_s_getreg((3 << 11) | 20) & 0xFu; }
; DI XcdBarrier xcd_barrier_post(unsigned* bar, volatile LAS unsigned* st) {
;     XcdBarrier b; b.bar = bar; b.x = xb_xcc_id(); b.st = st;
;     if (threadIdx.x == 0) (void)xb_add(&bar[XB_XCNT(b.x)], 1u);
;     return b;
; }
; DI void xcd_barrier_complete(unsigned* bar, unsigned x, unsigned& nloc, unsigned& nx) {
;     const unsigned G = gridDim.x * gridDim.y * gridDim.z;
;     unsigned sum, cnt, mine, sp = 0u;
;     for (;;) {
;         sum = 0u; cnt = 0u; mine = 0u;
; #pragma unroll
;         for (unsigned j = 0; j < 16; ++j) { const unsigned c = xb_ld(&bar[XB_XCNT(j)]); sum += c; cnt += (c > 0u) ? 1u : 0u; mine = (j == x) ? c : mine; }
; __global__ void __launch_bounds__(NTHREADS, 2) mega(Params p_, int ph_lo, int ph_hi) {
;     const Params& p = *(const Params*)__builtin_amdgcn_kernarg_segment_ptr();
;     extern __shared__ __attribute__((aligned(16))) char smem[];
;     cg::grid_group grid = cg::this_grid();
;     __shared__ uint4 xb_words;
;     if (threadIdx.x == 0) xb_words = make_uint4(0u, 0u, 0u, 0u);
;     __syncthreads();
;     XcdBarrier xb = xcd_barrier_post(p.bar, (volatile LAS unsigned*)&xb_words);
;     for (int ph = ph_lo; ph < ph_hi; ++ph) {
	s_mul_i32 s7, s7, s8
	s_mov_b32 s21, s75
	v_writelane_b32 v254, s13, 29
	s_add_u32 s12, s68, 0x200
	v_writelane_b32 v254, s7, 30
	s_addc_u32 s13, s69, 0
	v_writelane_b32 v254, s12, 31
	v_mov_b32_e32 v193, 0
	v_mbcnt_lo_u32_b32 v1, -1, 0
	v_writelane_b32 v254, s13, 32
	s_add_u32 s12, s68, 0x1000
	s_addc_u32 s13, s69, 0
	v_writelane_b32 v254, s12, 33
	v_mov_b32_e32 v201, 0x358637bd
	v_mov_b32_e32 v202, 0x3c0881c4
	v_writelane_b32 v254, s13, 34
	s_add_u32 s12, s68, 0x1100
	s_addc_u32 s13, s69, 0
	v_writelane_b32 v254, s12, 35
	v_mov_b32_e32 v203, 0xbab64f3b
	v_mov_b32_e32 v204, 0x7c
	v_writelane_b32 v254, s13, 36
	s_add_u32 s12, s68, 0x1200
	s_addc_u32 s13, s69, 0
	v_writelane_b32 v254, s12, 37
	v_mbcnt_hi_u32_b32 v205, -1, v1
	v_mov_b32_e32 v206, 0x3e38aa3b
	v_writelane_b32 v254, s13, 38
	s_add_u32 s12, s68, 0x1300
	s_addc_u32 s13, s69, 0
	v_writelane_b32 v254, s12, 39
	s_cmp_eq_u32 s3, 15
	v_mov_b32_e32 v207, 0x3e8293ee
	v_writelane_b32 v254, s13, 40
	s_cselect_b64 s[12:13], -1, 0
	v_writelane_b32 v254, s12, 41
	s_cmp_eq_u32 s3, 14
	v_mov_b32_e32 v208, 0x70
	v_writelane_b32 v254, s13, 42
	s_cselect_b64 s[12:13], -1, 0
	v_writelane_b32 v254, s12, 43
	s_cmp_eq_u32 s3, 13
	v_mov_b32_e32 v209, 0x7f800000
	v_writelane_b32 v254, s13, 44
	s_cselect_b64 s[12:13], -1, 0
	v_writelane_b32 v254, s12, 45
	s_cmp_eq_u32 s3, 12
	v_not_b32_e32 v211, 63
	v_writelane_b32 v254, s13, 46
	s_cselect_b64 s[12:13], -1, 0
	v_writelane_b32 v254, s12, 47
	s_cmp_eq_u32 s3, 11
	v_not_b32_e32 v212, 31
	v_writelane_b32 v254, s13, 48
	s_cselect_b64 s[12:13], -1, 0
	v_writelane_b32 v254, s12, 49
	s_cmp_eq_u32 s3, 10
	v_mov_b32_e32 v213, 0x7fc00000
	v_writelane_b32 v254, s13, 50
	s_cselect_b64 s[12:13], -1, 0
	v_writelane_b32 v254, s12, 51
	s_cmp_eq_u32 s3, 9
	s_movk_i32 s61, 0x800
	v_writelane_b32 v254, s13, 52
	s_cselect_b64 s[12:13], -1, 0
	v_writelane_b32 v254, s12, 53
	s_cmp_eq_u32 s3, 8
	s_movk_i32 s78, 0x2000
	v_writelane_b32 v254, s13, 54
	s_cselect_b64 s[12:13], -1, 0
	v_writelane_b32 v254, s12, 55
	s_cmp_eq_u32 s3, 7
	s_brev_b32 s86, 1
	v_writelane_b32 v254, s13, 56
	s_cselect_b64 s[12:13], -1, 0
	v_writelane_b32 v254, s12, 57
	s_cmp_eq_u32 s3, 6
	s_mov_b32 s87, 0x800000
	v_writelane_b32 v254, s13, 58
	s_cselect_b64 s[12:13], -1, 0
	v_writelane_b32 v254, s12, 59
	s_cmp_eq_u32 s3, 5
	s_mov_b32 s37, 0xbfb8aa3b
	v_writelane_b32 v254, s13, 60
	s_cselect_b64 s[12:13], -1, 0
	v_writelane_b32 v254, s12, 61
	s_cmp_eq_u32 s3, 4
	s_movk_i32 s33, 0x104
	v_writelane_b32 v254, s13, 62
	s_cselect_b64 s[12:13], -1, 0
	v_writelane_b32 v254, s12, 63
	s_cmp_eq_u32 s3, 3
	s_mov_b32 s31, 0x42ce8ed0
	v_writelane_b32 v255, s13, 0
	s_cselect_b64 s[12:13], -1, 0
	v_writelane_b32 v255, s12, 1
	s_cmp_eq_u32 s3, 2
	s_mov_b32 s67, 0xc2b17218
	v_writelane_b32 v255, s13, 2
	s_cselect_b64 s[12:13], -1, 0
	v_writelane_b32 v255, s12, 3
	s_cmp_eq_u32 s3, 1
	s_mov_b32 s83, 0x3c439041
	v_writelane_b32 v255, s13, 4
	s_cselect_b64 s[12:13], -1, 0
	v_writelane_b32 v255, s12, 5
	s_cmp_eq_u32 s3, 0
	s_mov_b32 s36, 0xdb629599
	v_writelane_b32 v255, s13, 6
	s_cselect_b64 s[12:13], -1, 0
	s_lshl_b32 s3, s3, 8
	s_add_u32 s3, s68, s3
	v_writelane_b32 v255, s12, 7
	s_addc_u32 s7, s69, 0
	s_mov_b32 s30, 0xf534ddc0
	v_writelane_b32 v255, s13, 8
	s_add_u32 s12, s3, 0x1400
	s_addc_u32 s13, s7, 0
	v_writelane_b32 v255, s12, 9
	s_mov_b32 s70, 0xfc2757d1
	s_mov_b32 s71, 0x4e441529
	v_writelane_b32 v255, s13, 10
	s_add_u32 s12, s3, 0x2400
	s_addc_u32 s13, s7, 0
	v_writelane_b32 v255, s12, 11
	s_movk_i32 s3, 0x3ff
	v_and_or_b32 v0, v0, s3, v200
	v_writelane_b32 v255, s13, 12
	s_add_u32 s12, s68, 0x3400
	s_addc_u32 s13, s69, 0
	v_writelane_b32 v255, s12, 13
	s_mov_b32 s72, 0xa2f9836e
	s_mov_b32 s73, 0x3fc90fda
	v_writelane_b32 v255, s13, 14
	s_add_u32 s12, s68, 0x3500
	s_addc_u32 s13, s69, 0
	v_writelane_b32 v255, s12, 15
	s_or_b32 s3, s9, s16
	s_lshl_b32 s3, s3, 6
	v_writelane_b32 v255, s13, 16
	v_writelane_b32 v255, s14, 17
	s_add_i32 s3, s3, 0x20000
	s_xor_b64 s[4:5], s[4:5], -1
	v_writelane_b32 v255, s15, 18
	v_writelane_b32 v255, s18, 19
	s_lshl_b32 s2, s2, 2
	s_lshl_b32 s74, s6, 2
	v_writelane_b32 v255, s19, 20
	v_writelane_b32 v255, s20, 21
	s_mov_b32 s18, 0x3f22f983
	s_mov_b32 s19, 0xbfc90fda
	v_writelane_b32 v255, s21, 22
	v_writelane_b32 v255, s16, 23
	v_writelane_b32 v255, s3, 24
	s_lshl_b32 s3, s10, 1
	v_writelane_b32 v255, s3, 25
	v_writelane_b32 v255, s4, 26
	s_lshl_b32 s3, s66, 3
	s_movk_i32 s20, 0x3000
	v_writelane_b32 v255, s5, 27
	v_writelane_b32 v255, s3, 28
	s_add_i32 s3, 32, 0x11000
	v_writelane_b32 v255, s3, 29
	v_writelane_b32 v255, s2, 30
	v_cmp_eq_u32_e64 s[4:5], 0, v0
	s_movk_i32 s21, 0x7ff
	v_writelane_b32 v255, s3, 31
	v_writelane_b32 v255, s4, 32
	s_brev_b32 s3, 18
	s_mov_b32 s2, 0xfe5163ab
	s_movk_i32 s82, 0x1f8
	s_mov_b64 s[26:27], 0x1000
	v_writelane_b32 v255, s5, 33
	s_mov_b64 s[76:77], 0x20000
	s_mov_b64 s[84:85], 0x240000
	s_mov_b64 s[14:15], 0x21000
	s_mov_b64 s[22:23], 0x241000
	s_mov_b64 s[10:11], 0x30000
	s_mov_b64 s[24:25], 0x360000
	s_mov_b64 s[38:39], 0x31000
	s_mov_b64 s[64:65], 0x361000
	s_mov_b64 s[16:17], 0x2000
	s_mov_b64 s[90:91], 0x3000
	s_mov_b64 s[92:93], 0x4000
	s_mov_b64 s[94:95], 0x5000
	s_mov_b64 s[80:81], 0x70000
	s_mov_b64 s[96:97], 0x71000
	s_mov_b64 s[12:13], 0x242000
	s_mov_b64 s[88:89], 0x243000
	s_branch .LBB0_11

; template <int Q>
; DI void attn_queue(const Params& p, int l, char* smem, int* s_unit, int cb) {
;     const bool ctxu = l < DEPTH - 1;
;     const int total = (Q == 0) ? (ctxu ? 576 : 512) : (Q == 1) ? (ctxu ? 960 : 768) : 768;
; DI void attn_phase(const Params& p, int l, char* smem, int cb) {
;     __shared__ int s_unit;
;     attn_queue<0>(p, l, smem, &s_unit, cb);
;     attn_queue<1>(p, l, smem, &s_unit, cb);
;     attn_queue<2>(p, l, smem, &s_unit, cb);
; }
.Lqo_bb70:
	s_cmp_lt_i32 s60, 3
	s_cselect_b64 s[44:45], -1, 0
	s_and_b64 s[4:5], s[44:45], exec
	s_movk_i32 s4, 0x240
	s_cselect_b32 s28, s4, 0x200
	s_lshl_b32 s4, s60, 6
	s_lshl_b32 s48, s60, 2
	s_ashr_i32 s5, s4, 31
	s_ashr_i32 s49, s48, 31
	s_ashr_i32 s61, s60, 31
	s_lshl_b64 s[46:47], s[4:5], 2
	v_readlane_b32 s4, v255, 44
	s_nop 0
	s_cmp_eq_u32 s4, 2
	s_cbranch_scc1 .LBB0_72
	v_readlane_b32 s4, v254, 0
	s_nop 0
	s_cmp_lt_u32 s4, 0x100
	s_cbranch_scc1 .LBB0_72
	v_writelane_b32 v255, 1, 44
	s_branch .LBB0_84

; DI void attn_phase(const Params& p, int l, char* smem, int cb) {
;     __shared__ int s_unit;
;     attn_queue<0>(p, l, smem, &s_unit, cb);
;     attn_queue<1>(p, l, smem, &s_unit, cb);
;     attn_queue<2>(p, l, smem, &s_unit, cb);
; }
.Lqo_after_q1:
	v_readlane_b32 s4, v255, 44
	s_nop 0
	s_cmp_eq_u32 s4, 1
	s_cbranch_scc0 .LBB0_109
	v_writelane_b32 v255, 2, 44
	s_branch .Lqo_bb70
.Lqo_after_q0:
	v_readlane_b32 s4, v255, 44
	s_nop 0
	s_cmp_eq_u32 s4, 2
	s_cbranch_scc0 .LBB0_84
	v_writelane_b32 v255, 0, 44
	s_movk_i32 s61, 0x800
	s_branch .LBB0_109
